# combo + grid barrier: followers wait on the top-level generation word directly, leader invalidate hoisted
# baseline (speedup 1.0000x reference)
.LBB0_62:
	s_or_b64 exec, exec, s[18:19]
	v_cvt_f32_u32_e32 v4, v2
	s_waitcnt vmcnt(0)
	v_readfirstlane_b32 s12, v3
	v_sub_u32_e32 v3, 0, v2
	v_rcp_iflag_f32_e32 v4, v4
	v_add_u32_e32 v5, s12, v1
	v_mul_f32_e32 v4, 0x4f7ffffe, v4
	v_cvt_u32_f32_e32 v4, v4
	v_mul_lo_u32 v1, v3, v4
	v_mul_hi_u32 v1, v4, v1
	v_add_u32_e32 v1, v4, v1
	v_mul_hi_u32 v1, v5, v1
	v_mul_lo_u32 v3, v1, v2
	v_sub_u32_e32 v3, v5, v3
	v_add_u32_e32 v4, 1, v1
	v_cmp_ge_u32_e32 vcc, v3, v2
	s_nop 1
	v_cndmask_b32_e32 v1, v1, v4, vcc
	v_sub_u32_e32 v4, v3, v2
	v_cndmask_b32_e32 v3, v3, v4, vcc
	v_add_u32_e32 v4, 1, v1
	v_cmp_ge_u32_e32 vcc, v3, v2
	v_add_u32_e32 v3, 1, v5
	s_nop 0
	v_cndmask_b32_e32 v1, v1, v4, vcc
	v_mul_lo_u32 v4, v2, v1
	v_add_u32_e32 v2, v4, v2
	v_cmp_ne_u32_e32 vcc, v3, v2
	s_and_saveexec_b64 s[12:13], vcc
	s_xor_b64 s[12:13], exec, s[12:13]
	s_cbranch_execz .LBB0_76
	s_waitcnt lgkmcnt(0)
	buffer_inv sc1
	v_mov_b32_e32 v0, 0x22207600
	global_load_dword v0, v0, s[24:25] sc1
	s_add_u32 s34, s24, 0x22207600
	s_addc_u32 s35, s25, 0
	s_waitcnt vmcnt(0)
	v_cmp_eq_u32_e32 vcc, v0, v1
	s_and_saveexec_b64 s[18:19], vcc
	s_cbranch_execz .LBB0_75
	s_add_u32 s30, s24, 0x22204300
	s_addc_u32 s31, s25, 0
	s_mov_b32 s56, 1
	s_mov_b64 s[36:37], 0
	v_mov_b32_e32 v0, 0
	s_branch .LBB0_66

.LBB0_160:
	s_or_b64 exec, exec, s[30:31]
	v_cvt_f32_u32_e32 v4, v2
	s_waitcnt vmcnt(0)
	v_readfirstlane_b32 s8, v3
	v_sub_u32_e32 v3, 0, v2
	v_rcp_iflag_f32_e32 v4, v4
	v_add_u32_e32 v5, s8, v1
	v_mul_f32_e32 v4, 0x4f7ffffe, v4
	v_cvt_u32_f32_e32 v4, v4
	v_mul_lo_u32 v1, v3, v4
	v_mul_hi_u32 v1, v4, v1
	v_add_u32_e32 v1, v4, v1
	v_mul_hi_u32 v1, v5, v1
	v_mul_lo_u32 v3, v1, v2
	v_sub_u32_e32 v3, v5, v3
	v_add_u32_e32 v4, 1, v1
	v_cmp_ge_u32_e32 vcc, v3, v2
	s_nop 1
	v_cndmask_b32_e32 v1, v1, v4, vcc
	v_sub_u32_e32 v4, v3, v2
	v_cndmask_b32_e32 v3, v3, v4, vcc
	v_add_u32_e32 v4, 1, v1
	v_cmp_ge_u32_e32 vcc, v3, v2
	v_add_u32_e32 v3, 1, v5
	s_nop 0
	v_cndmask_b32_e32 v1, v1, v4, vcc
	v_mul_lo_u32 v4, v2, v1
	v_add_u32_e32 v2, v4, v2
	v_cmp_ne_u32_e32 vcc, v3, v2
	s_and_saveexec_b64 s[8:9], vcc
	s_xor_b64 s[8:9], exec, s[8:9]
	s_cbranch_execz .LBB0_174
	s_waitcnt lgkmcnt(0)
	buffer_inv sc1
	v_mov_b32_e32 v0, 0x22207600
	global_load_dword v0, v0, s[24:25] sc1
	s_add_u32 s36, s24, 0x22207600
	s_addc_u32 s37, s25, 0
	s_waitcnt vmcnt(0)
	v_cmp_eq_u32_e32 vcc, v0, v1
	s_and_saveexec_b64 s[30:31], vcc
	s_cbranch_execz .LBB0_173
	s_add_u32 s34, s24, 0x22204300
	s_addc_u32 s35, s25, 0
	s_mov_b32 s54, 1
	s_mov_b64 s[40:41], 0
	v_mov_b32_e32 v0, 0
	s_branch .LBB0_164

.LBB0_592:
	s_or_b64 exec, exec, s[10:11]
	v_cvt_f32_u32_e32 v4, v2
	s_waitcnt vmcnt(0)
	v_readfirstlane_b32 s8, v3
	v_sub_u32_e32 v3, 0, v2
	v_rcp_iflag_f32_e32 v4, v4
	v_add_u32_e32 v5, s8, v1
	v_mul_f32_e32 v4, 0x4f7ffffe, v4
	v_cvt_u32_f32_e32 v4, v4
	v_mul_lo_u32 v1, v3, v4
	v_mul_hi_u32 v1, v4, v1
	v_add_u32_e32 v1, v4, v1
	v_mul_hi_u32 v1, v5, v1
	v_mul_lo_u32 v3, v1, v2
	v_sub_u32_e32 v3, v5, v3
	v_add_u32_e32 v4, 1, v1
	v_cmp_ge_u32_e32 vcc, v3, v2
	s_nop 1
	v_cndmask_b32_e32 v1, v1, v4, vcc
	v_sub_u32_e32 v4, v3, v2
	v_cndmask_b32_e32 v3, v3, v4, vcc
	v_add_u32_e32 v4, 1, v1
	v_cmp_ge_u32_e32 vcc, v3, v2
	v_add_u32_e32 v3, 1, v5
	s_nop 0
	v_cndmask_b32_e32 v1, v1, v4, vcc
	v_mul_lo_u32 v4, v2, v1
	v_add_u32_e32 v2, v4, v2
	v_cmp_ne_u32_e32 vcc, v3, v2
	s_and_saveexec_b64 s[8:9], vcc
	s_xor_b64 s[8:9], exec, s[8:9]
	s_cbranch_execz .LBB0_606
	s_waitcnt lgkmcnt(0)
	buffer_inv sc1
	v_mov_b32_e32 v0, 0x22207600
	global_load_dword v0, v0, s[24:25] sc1
	s_add_u32 s34, s24, 0x22207600
	s_addc_u32 s35, s25, 0
	s_waitcnt vmcnt(0)
	v_cmp_eq_u32_e32 vcc, v0, v1
	s_and_saveexec_b64 s[10:11], vcc
	s_cbranch_execz .LBB0_605
	s_add_u32 s30, s24, 0x22204300
	s_addc_u32 s31, s25, 0
	s_mov_b32 s50, 1
	s_mov_b64 s[36:37], 0
	v_mov_b32_e32 v0, 0
	s_branch .LBB0_596

.LBB0_863:
	s_or_b64 exec, exec, s[10:11]
	v_cvt_f32_u32_e32 v4, v2
	s_waitcnt vmcnt(0)
	v_readfirstlane_b32 s7, v3
	v_sub_u32_e32 v3, 0, v2
	v_rcp_iflag_f32_e32 v4, v4
	v_add_u32_e32 v5, s7, v1
	v_mul_f32_e32 v4, 0x4f7ffffe, v4
	v_cvt_u32_f32_e32 v4, v4
	v_mul_lo_u32 v1, v3, v4
	v_mul_hi_u32 v1, v4, v1
	v_add_u32_e32 v1, v4, v1
	v_mul_hi_u32 v1, v5, v1
	v_mul_lo_u32 v3, v1, v2
	v_sub_u32_e32 v3, v5, v3
	v_add_u32_e32 v4, 1, v1
	v_cmp_ge_u32_e32 vcc, v3, v2
	s_nop 1
	v_cndmask_b32_e32 v1, v1, v4, vcc
	v_sub_u32_e32 v4, v3, v2
	v_cndmask_b32_e32 v3, v3, v4, vcc
	v_add_u32_e32 v4, 1, v1
	v_cmp_ge_u32_e32 vcc, v3, v2
	v_add_u32_e32 v3, 1, v5
	s_nop 0
	v_cndmask_b32_e32 v1, v1, v4, vcc
	v_mul_lo_u32 v4, v2, v1
	v_add_u32_e32 v2, v4, v2
	v_cmp_ne_u32_e32 vcc, v3, v2
	s_and_saveexec_b64 s[8:9], vcc
	s_xor_b64 s[8:9], exec, s[8:9]
	s_cbranch_execz .LBB0_877
	s_waitcnt lgkmcnt(0)
	buffer_inv sc1
	v_mov_b32_e32 v0, 0x22207600
	global_load_dword v0, v0, s[24:25] sc1
	s_add_u32 s16, s24, 0x22207600
	s_addc_u32 s17, s25, 0
	s_waitcnt vmcnt(0)
	v_cmp_eq_u32_e32 vcc, v0, v1
	s_and_saveexec_b64 s[10:11], vcc
	s_cbranch_execz .LBB0_876
	s_add_u32 s14, s24, 0x22204300
	s_addc_u32 s15, s25, 0
	s_mov_b32 s46, 1
	s_mov_b64 s[30:31], 0
	v_mov_b32_e32 v0, 0
	s_branch .LBB0_867

.LBB0_1159:
	s_or_b64 exec, exec, s[10:11]
	v_cvt_f32_u32_e32 v4, v2
	s_waitcnt vmcnt(0)
	v_readfirstlane_b32 s7, v3
	v_sub_u32_e32 v3, 0, v2
	v_rcp_iflag_f32_e32 v4, v4
	v_add_u32_e32 v5, s7, v1
	v_mul_f32_e32 v4, 0x4f7ffffe, v4
	v_cvt_u32_f32_e32 v4, v4
	v_mul_lo_u32 v1, v3, v4
	v_mul_hi_u32 v1, v4, v1
	v_add_u32_e32 v1, v4, v1
	v_mul_hi_u32 v1, v5, v1
	v_mul_lo_u32 v3, v1, v2
	v_sub_u32_e32 v3, v5, v3
	v_add_u32_e32 v4, 1, v1
	v_cmp_ge_u32_e32 vcc, v3, v2
	s_nop 1
	v_cndmask_b32_e32 v1, v1, v4, vcc
	v_sub_u32_e32 v4, v3, v2
	v_cndmask_b32_e32 v3, v3, v4, vcc
	v_add_u32_e32 v4, 1, v1
	v_cmp_ge_u32_e32 vcc, v3, v2
	v_add_u32_e32 v3, 1, v5
	s_nop 0
	v_cndmask_b32_e32 v1, v1, v4, vcc
	v_mul_lo_u32 v4, v2, v1
	v_add_u32_e32 v2, v4, v2
	v_cmp_ne_u32_e32 vcc, v3, v2
	s_and_saveexec_b64 s[8:9], vcc
	s_xor_b64 s[8:9], exec, s[8:9]
	s_cbranch_execz .LBB0_1173
	s_waitcnt lgkmcnt(0)
	buffer_inv sc1
	v_mov_b32_e32 v0, 0x22207600
	global_load_dword v0, v0, s[24:25] sc1
	s_add_u32 s16, s24, 0x22207600
	s_addc_u32 s17, s25, 0
	s_waitcnt vmcnt(0)
	v_cmp_eq_u32_e32 vcc, v0, v1
	s_and_saveexec_b64 s[10:11], vcc
	s_cbranch_execz .LBB0_1172
	s_add_u32 s14, s24, 0x22204300
	s_addc_u32 s15, s25, 0
	s_mov_b32 s42, 1
	s_mov_b64 s[20:21], 0
	v_mov_b32_e32 v0, 0
	s_branch .LBB0_1163

.LBB0_1368:
	s_or_b64 exec, exec, s[10:11]
	v_cvt_f32_u32_e32 v4, v2
	s_waitcnt vmcnt(0)
	v_readfirstlane_b32 s7, v3
	v_sub_u32_e32 v3, 0, v2
	v_rcp_iflag_f32_e32 v4, v4
	v_add_u32_e32 v5, s7, v1
	v_mul_f32_e32 v4, 0x4f7ffffe, v4
	v_cvt_u32_f32_e32 v4, v4
	v_mul_lo_u32 v1, v3, v4
	v_mul_hi_u32 v1, v4, v1
	v_add_u32_e32 v1, v4, v1
	v_mul_hi_u32 v1, v5, v1
	v_mul_lo_u32 v3, v1, v2
	v_sub_u32_e32 v3, v5, v3
	v_add_u32_e32 v4, 1, v1
	v_cmp_ge_u32_e32 vcc, v3, v2
	s_nop 1
	v_cndmask_b32_e32 v1, v1, v4, vcc
	v_sub_u32_e32 v4, v3, v2
	v_cndmask_b32_e32 v3, v3, v4, vcc
	v_add_u32_e32 v4, 1, v1
	v_cmp_ge_u32_e32 vcc, v3, v2
	v_add_u32_e32 v3, 1, v5
	s_nop 0
	v_cndmask_b32_e32 v1, v1, v4, vcc
	v_mul_lo_u32 v4, v2, v1
	v_add_u32_e32 v2, v4, v2
	v_cmp_ne_u32_e32 vcc, v3, v2
	s_and_saveexec_b64 s[8:9], vcc
	s_xor_b64 s[8:9], exec, s[8:9]
	s_cbranch_execz .LBB0_1382
	s_waitcnt lgkmcnt(0)
	buffer_inv sc1
	v_mov_b32_e32 v0, 0x22207600
	global_load_dword v0, v0, s[24:25] sc1
	s_add_u32 s16, s24, 0x22207600
	s_addc_u32 s17, s25, 0
	s_waitcnt vmcnt(0)
	v_cmp_eq_u32_e32 vcc, v0, v1
	s_and_saveexec_b64 s[10:11], vcc
	s_cbranch_execz .LBB0_1381
	s_add_u32 s14, s24, 0x22204300
	s_addc_u32 s15, s25, 0
	s_mov_b32 s7, 1
	s_mov_b64 s[20:21], 0
	v_mov_b32_e32 v0, 0
	s_branch .LBB0_1372

.LBB0_1483:
	s_or_b64 exec, exec, s[6:7]
	v_cvt_f32_u32_e32 v4, v2
	s_waitcnt vmcnt(0)
	v_readfirstlane_b32 s4, v3
	v_sub_u32_e32 v3, 0, v2
	v_rcp_iflag_f32_e32 v4, v4
	v_add_u32_e32 v5, s4, v1
	v_mul_f32_e32 v4, 0x4f7ffffe, v4
	v_cvt_u32_f32_e32 v4, v4
	v_mul_lo_u32 v1, v3, v4
	v_mul_hi_u32 v1, v4, v1
	v_add_u32_e32 v1, v4, v1
	v_mul_hi_u32 v1, v5, v1
	v_mul_lo_u32 v3, v1, v2
	v_sub_u32_e32 v3, v5, v3
	v_add_u32_e32 v4, 1, v1
	v_cmp_ge_u32_e32 vcc, v3, v2
	s_nop 1
	v_cndmask_b32_e32 v1, v1, v4, vcc
	v_sub_u32_e32 v4, v3, v2
	v_cndmask_b32_e32 v3, v3, v4, vcc
	v_add_u32_e32 v4, 1, v1
	v_cmp_ge_u32_e32 vcc, v3, v2
	v_add_u32_e32 v3, 1, v5
	s_nop 0
	v_cndmask_b32_e32 v1, v1, v4, vcc
	v_mul_lo_u32 v4, v2, v1
	v_add_u32_e32 v2, v4, v2
	v_cmp_ne_u32_e32 vcc, v3, v2
	s_and_saveexec_b64 s[4:5], vcc
	s_xor_b64 s[4:5], exec, s[4:5]
	s_cbranch_execz .LBB0_1497
	s_waitcnt lgkmcnt(0)
	buffer_inv sc1
	v_mov_b32_e32 v0, 0x22207600
	global_load_dword v0, v0, s[24:25] sc1
	s_add_u32 s10, s24, 0x22207600
	s_addc_u32 s11, s25, 0
	s_waitcnt vmcnt(0)
	v_cmp_eq_u32_e32 vcc, v0, v1
	s_and_saveexec_b64 s[6:7], vcc
	s_cbranch_execz .LBB0_1496
	s_add_u32 s8, s24, 0x22204300
	s_addc_u32 s9, s25, 0
	s_mov_b32 s22, 1
	s_mov_b64 s[12:13], 0
	v_mov_b32_e32 v0, 0
	s_branch .LBB0_1487
